# v12 + MoBA chunk loops: K fragment LDS reads issued together with counted lgkmcnt, redundant self-max canonicalizations removed from the row-max tree
# speedup vs baseline: 1.0114x; 1.0102x over previous
; #define LAS __attribute__((address_space(3)))
; __device__ __forceinline__ float xor32_max(float v) { auto rr = __builtin_amdgcn_permlane32_swap(__float_as_uint(v), __float_as_uint(v), false, false); return fmaxf(__uint_as_float(rr[0]), __uint_as_float(rr[1])); }
; __device__ __forceinline__ int crow(int r, int h) { return (r & 3) + 8 * (r >> 2) + 4 * h; }
; __device__ __forceinline__ void soft_compute_lds(SoftState& st, const bf16x8 (&qf)[4], const LAS unsigned char* kc, const LAS unsigned char* vc, int k0, int qp, bool lane_ok, bool diag, const WaveCtx& c) {
;     bf16x8 kf[4];
; #pragma unroll
;     for (int ks = 0; ks < 4; ++ks) kf[ks] = *(const LAS bf16x8*)(kc + c.q * VROW + ks * 32 + c.h * 16);
;     f32x16 s = qk_ref(kf, qf, st.negm);
;     if (diag) {
; #pragma unroll
;         for (int r = 0; r < 16; ++r) { const int kp = k0 + crow(r, c.h); s[r] = (kp <= qp) ? s[r] : -1e30f; }
;     } else if (__ballot(!lane_ok) != 0ull) {
; #pragma unroll
;         for (int r = 0; r < 16; ++r) s[r] = lane_ok ? s[r] : -1e30f;
;     }
;     float mx = fmaxf(fmaxf(s[0], s[1]), fmaxf(s[2], s[3]));
; #pragma unroll
;     for (int r = 4; r < 16; r += 4) mx = fmaxf(mx, fmaxf(fmaxf(s[r], s[r + 1]), fmaxf(s[r + 2], s[r + 3])));
;     mx = xor32_max(mx);
;     if (__ballot(mx > 8.0f) != 0ull) {
;         const float d = fmaxf(mx, 0.f), scl = __builtin_amdgcn_exp2f(-d);
;         st.l *= scl; st.m += d;
;         const float nm = -st.m;
; #pragma unroll
;         for (int r = 0; r < 16; ++r) { st.o[0][r] *= scl; st.o[1][r] *= scl; s[r] -= d; st.negm[r] = nm; }
;     }
.LBB0_492:
	v_add_u32_e32 v163, s97, v160
	ds_read_b128 v[164:167], v163
	ds_read_b128 v[238:241], v163 offset:32
	ds_read_b128 v[250:253], v163 offset:64
	s_waitcnt lgkmcnt(2)
	v_mfma_f32_32x32x16_bf16 v[98:113], v[164:167], v[114:117], v[82:97]
	ds_read_b128 v[164:167], v163 offset:96
	v_cndmask_b32_e64 v163, 0, 1, s[34:35]
	v_cmp_ne_u32_e32 vcc, 0, v163
	s_waitcnt lgkmcnt(2)
	v_mfma_f32_32x32x16_bf16 v[98:113], v[238:241], v[118:121], v[98:113]
	s_waitcnt lgkmcnt(1)
	v_mfma_f32_32x32x16_bf16 v[98:113], v[250:253], v[122:125], v[98:113]
	s_waitcnt lgkmcnt(0)
	v_mfma_f32_32x32x16_bf16 v[98:113], v[164:167], v[126:129], v[98:113]
	s_cbranch_vccz .LBB0_494
	s_nop 10
	v_cndmask_b32_e64 v98, v98, v244, s[34:35]
	v_cndmask_b32_e64 v99, v99, v244, s[34:35]
	v_cndmask_b32_e64 v100, v100, v244, s[34:35]
	v_cndmask_b32_e64 v101, v101, v244, s[34:35]
	v_cndmask_b32_e64 v102, v102, v244, s[34:35]
	v_cndmask_b32_e64 v103, v103, v244, s[34:35]
	v_cndmask_b32_e64 v104, v104, v244, s[34:35]
	v_cndmask_b32_e64 v105, v105, v244, s[34:35]
	v_cndmask_b32_e64 v106, v106, v244, s[34:35]
	v_cndmask_b32_e64 v107, v107, v244, s[34:35]
	v_cndmask_b32_e64 v108, v108, v244, s[34:35]
	v_cndmask_b32_e64 v109, v109, v244, s[34:35]
	v_cndmask_b32_e64 v110, v110, v244, s[34:35]
	v_cndmask_b32_e64 v111, v111, v244, s[34:35]
	v_cndmask_b32_e64 v112, v112, v244, s[34:35]
	v_cndmask_b32_e64 v113, v113, v244, s[34:35]
.LBB0_494:
	s_nop 10
	v_max_f32_e32 v163, v98, v99
	v_max_f32_e32 v164, v100, v101
	v_max_f32_e32 v165, v104, v105
	v_max3_f32 v165, v102, v103, v165
	v_max3_f32 v163, v163, v164, v165
	v_max_f32_e32 v164, v108, v109
	v_max_f32_e32 v165, v112, v113
	v_max3_f32 v164, v106, v107, v164
	v_max3_f32 v165, v110, v111, v165
	v_max3_f32 v163, v163, v164, v165
	v_mov_b32_e32 v164, v163
	s_nop 1
	v_permlane32_swap_b32_e32 v163, v164
	v_max_f32_e32 v163, v163, v164
	v_cmp_lt_f32_e32 vcc, s70, v163
	s_cbranch_vccz .LBB0_491
	v_max_f32_e32 v82, v163, v163
	v_max_f32_e32 v84, 0, v82
	v_exp_f32_e64 v86, -v84
	v_add_f32_e32 v161, v161, v84
	v_xor_b32_e32 v82, 0x80000000, v161
	v_pk_add_f32 v[98:99], v[98:99], v[84:85] op_sel_hi:[1,0] neg_lo:[0,1] neg_hi:[0,1]
	v_mul_f32_e32 v162, v162, v86
	v_pk_add_f32 v[100:101], v[100:101], v[84:85] op_sel_hi:[1,0] neg_lo:[0,1] neg_hi:[0,1]
	v_pk_add_f32 v[102:103], v[102:103], v[84:85] op_sel_hi:[1,0] neg_lo:[0,1] neg_hi:[0,1]
	v_pk_add_f32 v[104:105], v[104:105], v[84:85] op_sel_hi:[1,0] neg_lo:[0,1] neg_hi:[0,1]
	v_pk_add_f32 v[106:107], v[106:107], v[84:85] op_sel_hi:[1,0] neg_lo:[0,1] neg_hi:[0,1]
	v_pk_add_f32 v[108:109], v[108:109], v[84:85] op_sel_hi:[1,0] neg_lo:[0,1] neg_hi:[0,1]
	v_pk_add_f32 v[110:111], v[110:111], v[84:85] op_sel_hi:[1,0] neg_lo:[0,1] neg_hi:[0,1]
	v_pk_mul_f32 v[80:81], v[80:81], v[86:87] op_sel_hi:[1,0]
	v_pk_mul_f32 v[78:79], v[78:79], v[86:87] op_sel_hi:[1,0]
	v_pk_mul_f32 v[76:77], v[76:77], v[86:87] op_sel_hi:[1,0]
	v_pk_mul_f32 v[74:75], v[74:75], v[86:87] op_sel_hi:[1,0]
	v_pk_mul_f32 v[72:73], v[72:73], v[86:87] op_sel_hi:[1,0]
	v_pk_mul_f32 v[70:71], v[70:71], v[86:87] op_sel_hi:[1,0]
	v_pk_mul_f32 v[68:69], v[68:69], v[86:87] op_sel_hi:[1,0]
	v_pk_mul_f32 v[66:67], v[66:67], v[86:87] op_sel_hi:[1,0]
	v_pk_mul_f32 v[62:63], v[62:63], v[86:87] op_sel_hi:[1,0]
	v_pk_mul_f32 v[60:61], v[60:61], v[86:87] op_sel_hi:[1,0]
	v_pk_mul_f32 v[58:59], v[58:59], v[86:87] op_sel_hi:[1,0]
	v_pk_mul_f32 v[56:57], v[56:57], v[86:87] op_sel_hi:[1,0]
	v_pk_mul_f32 v[54:55], v[54:55], v[86:87] op_sel_hi:[1,0]
	v_pk_mul_f32 v[52:53], v[52:53], v[86:87] op_sel_hi:[1,0]
	v_pk_mul_f32 v[50:51], v[50:51], v[86:87] op_sel_hi:[1,0]
	v_pk_mul_f32 v[48:49], v[48:49], v[86:87] op_sel_hi:[1,0]
	v_pk_add_f32 v[112:113], v[112:113], v[84:85] op_sel_hi:[1,0] neg_lo:[0,1] neg_hi:[0,1]
	v_mov_b32_e32 v83, v82
	v_mov_b32_e32 v84, v82
	v_mov_b32_e32 v85, v82
	v_mov_b32_e32 v86, v82
	v_mov_b32_e32 v87, v82
	v_mov_b32_e32 v88, v82
	v_mov_b32_e32 v89, v82
	v_mov_b32_e32 v90, v82
	v_mov_b32_e32 v91, v82
	v_mov_b32_e32 v92, v82
	v_mov_b32_e32 v93, v82
	v_mov_b32_e32 v94, v82
	v_mov_b32_e32 v95, v82
	v_mov_b32_e32 v96, v82
	v_mov_b32_e32 v97, v82
	s_branch .LBB0_491

; #define LAS __attribute__((address_space(3)))
; __device__ __forceinline__ float xor32_max(float v) { auto rr = __builtin_amdgcn_permlane32_swap(__float_as_uint(v), __float_as_uint(v), false, false); return fmaxf(__uint_as_float(rr[0]), __uint_as_float(rr[1])); }
; __device__ __forceinline__ int crow(int r, int h) { return (r & 3) + 8 * (r >> 2) + 4 * h; }
; __device__ __forceinline__ void soft_compute_lds(SoftState& st, const bf16x8 (&qf)[4], const LAS unsigned char* kc, const LAS unsigned char* vc, int k0, int qp, bool lane_ok, bool diag, const WaveCtx& c) {
;     bf16x8 kf[4];
; #pragma unroll
;     for (int ks = 0; ks < 4; ++ks) kf[ks] = *(const LAS bf16x8*)(kc + c.q * VROW + ks * 32 + c.h * 16);
;     f32x16 s = qk_ref(kf, qf, st.negm);
;     if (diag) {
; #pragma unroll
;         for (int r = 0; r < 16; ++r) { const int kp = k0 + crow(r, c.h); s[r] = (kp <= qp) ? s[r] : -1e30f; }
;     } else if (__ballot(!lane_ok) != 0ull) {
; #pragma unroll
;         for (int r = 0; r < 16; ++r) s[r] = lane_ok ? s[r] : -1e30f;
;     }
;     float mx = fmaxf(fmaxf(s[0], s[1]), fmaxf(s[2], s[3]));
; #pragma unroll
;     for (int r = 4; r < 16; r += 4) mx = fmaxf(mx, fmaxf(fmaxf(s[r], s[r + 1]), fmaxf(s[r + 2], s[r + 3])));
;     mx = xor32_max(mx);
;     if (__ballot(mx > 8.0f) != 0ull) {
;         const float d = fmaxf(mx, 0.f), scl = __builtin_amdgcn_exp2f(-d);
;         st.l *= scl; st.m += d;
;         const float nm = -st.m;
; #pragma unroll
;         for (int r = 0; r < 16; ++r) { st.o[0][r] *= scl; st.o[1][r] *= scl; s[r] -= d; st.negm[r] = nm; }
;     }
.LBB0_500:
	s_cmp_gt_i32 s34, s77
	s_cbranch_scc1 .LBB0_499
	s_nop 3
	v_add_u32_e32 v70, s35, v160
	ds_read_b128 v[66:69], v70
	ds_read_b128 v[238:241], v70 offset:32
	ds_read_b128 v[250:253], v70 offset:64
	s_cmp_lg_u32 s77, s34
	s_waitcnt lgkmcnt(2)
	v_mfma_f32_32x32x16_bf16 v[48:63], v[66:69], v[114:117], v[32:47]
	ds_read_b128 v[66:69], v70 offset:96
	s_waitcnt lgkmcnt(2)
	v_mfma_f32_32x32x16_bf16 v[48:63], v[238:241], v[118:121], v[48:63]
	s_waitcnt lgkmcnt(1)
	v_mfma_f32_32x32x16_bf16 v[48:63], v[250:253], v[122:125], v[48:63]
	s_waitcnt lgkmcnt(0)
	v_mfma_f32_32x32x16_bf16 v[48:63], v[66:69], v[126:129], v[48:63]
	s_cbranch_scc1 .LBB0_503
	s_nop 10
	v_cndmask_b32_e64 v48, v48, v244, s[0:1]
	v_cndmask_b32_e64 v49, v244, v49, s[2:3]
	v_cndmask_b32_e64 v50, v50, v244, s[4:5]
	v_cndmask_b32_e64 v51, v51, v244, s[6:7]
	v_cndmask_b32_e64 v52, v52, v244, s[8:9]
	v_cndmask_b32_e64 v53, v53, v244, s[10:11]
	v_cndmask_b32_e64 v54, v54, v244, s[12:13]
	v_cndmask_b32_e64 v55, v55, v244, s[14:15]
	v_cndmask_b32_e64 v56, v56, v244, s[16:17]
	v_cndmask_b32_e64 v57, v57, v244, s[18:19]
	v_cndmask_b32_e64 v58, v58, v244, s[20:21]
	v_cndmask_b32_e64 v59, v59, v244, s[22:23]
	v_cndmask_b32_e64 v60, v60, v244, s[24:25]
	v_cndmask_b32_e64 v61, v61, v244, s[26:27]
	v_cndmask_b32_e64 v62, v62, v244, s[28:29]
	v_cndmask_b32_e64 v63, v63, v244, s[30:31]
.LBB0_503:
	s_nop 10
	v_max_f32_e32 v66, v48, v49
	v_max_f32_e32 v67, v50, v51
	v_max_f32_e32 v68, v54, v55
	v_max3_f32 v68, v52, v53, v68
	v_max3_f32 v66, v66, v67, v68
	v_max_f32_e32 v67, v58, v59
	v_max_f32_e32 v68, v62, v63
	v_max3_f32 v67, v56, v57, v67
	v_max3_f32 v68, v60, v61, v68
	v_max3_f32 v66, v66, v67, v68
	v_mov_b32_e32 v67, v66
	s_nop 1
	v_permlane32_swap_b32_e32 v66, v67
	v_max_f32_e32 v66, v66, v67
	v_cmp_lt_f32_e32 vcc, s70, v66
	s_cbranch_vccz .LBB0_498
	v_max_f32_e32 v32, v66, v66
	v_max_f32_e32 v34, 0, v32
	v_exp_f32_e64 v36, -v34
	v_add_f32_e32 v158, v158, v34
	v_xor_b32_e32 v32, 0x80000000, v158
	v_pk_add_f32 v[48:49], v[48:49], v[34:35] op_sel_hi:[1,0] neg_lo:[0,1] neg_hi:[0,1]
	v_mul_f32_e32 v64, v64, v36
	v_pk_add_f32 v[50:51], v[50:51], v[34:35] op_sel_hi:[1,0] neg_lo:[0,1] neg_hi:[0,1]
	v_pk_add_f32 v[52:53], v[52:53], v[34:35] op_sel_hi:[1,0] neg_lo:[0,1] neg_hi:[0,1]
	v_pk_add_f32 v[54:55], v[54:55], v[34:35] op_sel_hi:[1,0] neg_lo:[0,1] neg_hi:[0,1]
	v_pk_add_f32 v[56:57], v[56:57], v[34:35] op_sel_hi:[1,0] neg_lo:[0,1] neg_hi:[0,1]
	v_pk_add_f32 v[58:59], v[58:59], v[34:35] op_sel_hi:[1,0] neg_lo:[0,1] neg_hi:[0,1]
	v_pk_add_f32 v[60:61], v[60:61], v[34:35] op_sel_hi:[1,0] neg_lo:[0,1] neg_hi:[0,1]
	v_pk_mul_f32 v[14:15], v[14:15], v[36:37] op_sel_hi:[1,0]
	v_pk_mul_f32 v[12:13], v[12:13], v[36:37] op_sel_hi:[1,0]
	v_pk_mul_f32 v[10:11], v[10:11], v[36:37] op_sel_hi:[1,0]
	v_pk_mul_f32 v[8:9], v[8:9], v[36:37] op_sel_hi:[1,0]
	v_pk_mul_f32 v[6:7], v[6:7], v[36:37] op_sel_hi:[1,0]
	v_pk_mul_f32 v[4:5], v[4:5], v[36:37] op_sel_hi:[1,0]
	v_pk_mul_f32 v[2:3], v[2:3], v[36:37] op_sel_hi:[1,0]
	v_pk_mul_f32 v[0:1], v[0:1], v[36:37] op_sel_hi:[1,0]
	v_pk_mul_f32 v[30:31], v[30:31], v[36:37] op_sel_hi:[1,0]
	v_pk_mul_f32 v[28:29], v[28:29], v[36:37] op_sel_hi:[1,0]
	v_pk_mul_f32 v[26:27], v[26:27], v[36:37] op_sel_hi:[1,0]
	v_pk_mul_f32 v[24:25], v[24:25], v[36:37] op_sel_hi:[1,0]
	v_pk_mul_f32 v[22:23], v[22:23], v[36:37] op_sel_hi:[1,0]
	v_pk_mul_f32 v[20:21], v[20:21], v[36:37] op_sel_hi:[1,0]
	v_pk_mul_f32 v[18:19], v[18:19], v[36:37] op_sel_hi:[1,0]
	v_pk_mul_f32 v[16:17], v[16:17], v[36:37] op_sel_hi:[1,0]
	v_pk_add_f32 v[62:63], v[62:63], v[34:35] op_sel_hi:[1,0] neg_lo:[0,1] neg_hi:[0,1]
	v_mov_b32_e32 v33, v32
	v_mov_b32_e32 v34, v32
	v_mov_b32_e32 v35, v32
	v_mov_b32_e32 v36, v32
	v_mov_b32_e32 v37, v32
	v_mov_b32_e32 v38, v32
	v_mov_b32_e32 v39, v32
	v_mov_b32_e32 v40, v32
	v_mov_b32_e32 v41, v32
	v_mov_b32_e32 v42, v32
	v_mov_b32_e32 v43, v32
	v_mov_b32_e32 v44, v32
	v_mov_b32_e32 v45, v32
	v_mov_b32_e32 v46, v32
	v_mov_b32_e32 v47, v32
	s_branch .LBB0_498
